# hyena MFMA loop: waves 4-7 delayed by ~half an iteration (s_sleep 4) at loop entry - stagger of SIMD partners (on top of v23)
# baseline (speedup 1.0000x reference)
.LBB0_500:
	s_or_b64 exec, exec, s[0:1]
	v_and_b32_e32 v0, 31, v77
	s_ashr_i32 s4, s10, 2
	v_bfe_u32 v79, v77, 4, 1
	s_and_b32 s0, s4, -16
	v_bfi_b32 v80, -16, s4, v77
	v_lshlrev_b32_e32 v0, 2, v0
	v_bfe_u32 v78, v77, 5, 1
	v_mul_u32_u24_e32 v2, 0x5a00, v79
	v_mul_lo_u32 v3, v80, s57
	v_readlane_b32 s1, v253, 46
	v_sub_u32_e32 v4, 0, v0
	s_addk_i32 s0, 0xff81
	v_add3_u32 v81, s1, v2, v3
	v_lshl_add_u32 v4, v78, 5, v4
	s_lshl_b32 s1, s0, 8
	v_lshlrev_b32_e32 v3, 4, v78
	v_subrev_u32_e32 v4, s1, v4
	s_mul_i32 s1, s0, 0xffffff70
	v_add_u32_e32 v5, 0x8000, v4
	v_add3_u32 v6, v81, v3, s1
	s_waitcnt lgkmcnt(0)
	s_barrier
	ds_read2_b32 v[38:39], v5 offset0:63 offset1:65
	ds_read2_b32 v[40:41], v5 offset0:67 offset1:69
	ds_read2_b32 v[34:35], v5 offset0:47 offset1:49
	ds_read2_b32 v[36:37], v5 offset0:51 offset1:53
	ds_read_b128 v[70:73], v6 offset:2304
	ds_read_b128 v[58:61], v6 offset:2336
	ds_read_b128 v[50:53], v6 offset:2368
	ds_read_b128 v[46:49], v6 offset:2400
	ds_read2_b32 v[42:43], v5 offset0:31 offset1:33
	ds_read2_b32 v[44:45], v5 offset0:35 offset1:37
	ds_read2_b32 v[54:55], v5 offset0:15 offset1:17
	ds_read2_b32 v[56:57], v5 offset0:19 offset1:21
	v_add_u32_e32 v6, 0x7e00, v4
	v_add_u32_e32 v4, 0x7c00, v4
	ds_read2_b32 v[62:63], v6 offset0:127 offset1:129
	ds_read2_b32 v[64:65], v5 offset0:3 offset1:5
	ds_read2_b32 v[66:67], v4 offset0:239 offset1:241
	ds_read2_b32 v[68:69], v4 offset0:243 offset1:245
	s_or_b32 s1, s4, 15
	s_cmp_lt_i32 s0, s1
	v_mov_b32_e32 v33, 0
	s_cbranch_scc0 .LBB0_503
	v_readfirstlane_b32 s5, v77
	s_cmpk_lt_u32 s5, 0x100
	s_cbranch_scc1 .Lhy_stagger_skip
	s_sleep 4
